# baseline (speedup 1.0000x reference)
; #define tidx() tidx_(wv_)
; #define WAIT_V(n) asm volatile("s_waitcnt vmcnt(" #n ")" ::: "memory")
; __device__ __forceinline__ void gemm_tile(const GemmArgs& ga, int wgid, int next_wgid, bool prefetched, u16* shm, unsigned char* ws, int wv_) {
;     ...
;   const int tid = tidx();
;   const u16* A = ga.A;
;   const u16* Bt = ga.Bt;
;   const int lda = ga.lda, ldb = ga.ldb;
;   unsigned aoff0, aoff1, boff0, boff1;
;   {
;     int r0, c0, r1, c1;
;     stage_rc(tid * 16, r0, c0);
;     stage_rc(tid * 16 + 8192, r1, c1);
;     aoff0 = (unsigned)(r0 * lda + c0) * 2u; aoff1 = (unsigned)(r1 * lda + c1) * 2u;
;     boff0 = (unsigned)(r0 * ldb + c0) * 2u; boff1 = (unsigned)(r1 * ldb + c1) * 2u;
;   }
;   const int nM = ga.nM, nN = ga.nN, nwg = nM * nN;
;   auto tilemap = [&](int w, int& o_brow, int& o_bcol, int& o_pn) {
;     int q = nwg / NXCD, r = nwg % NXCD, xcd = w % NXCD, off = w / NXCD;
;     w = (xcd < r ? xcd * (q + 1) : r * (q + 1) + (xcd - r) * q) + off;
;     int nig = WGM * nN, gid = w / nig, fm = gid * WGM, gsz = min(nM - fm, WGM);
;     int pm = fm + ((w % nig) % gsz);
;     o_pn = (w % nig) / gsz;
;     o_brow = pm * BM;
;     o_bcol = o_pn * BM;
;   };
;   int brow, bcol, pn;
;   tilemap(wgid, brow, bcol, pn);
;   int ks = 0;
;   if (ga.epi & EPI_KSPLIT4) { ks = pn & 3; pn >>= 2; bcol = pn * BM; }
;   const char* pa;
;   const char* pb;
;   int wr;
;   {
;     int wid = tid >> 6, lane = tid & 63, wc = wid & 3, fr = lane & 15, fq = lane >> 4;
;     wr = wid >> 2;
;     int pt = (fr * 64 + fq * 16) ^ ((fr >> 3) << 5);
;     pa = (const char*)shm + wr * 8192 + pt;
;     pb = (const char*)shm + 65536 + wc * 4096 + pt;
;   }
;   if (ga.epi == EPI_LORA) {
;     int koff = (pn >= 20) ? 256 : 0;
;     A += koff;
;     Bt += koff;
;   }
;   if (ga.epi & EPI_KSPLIT4) { A += ks * ga.K; Bt += ks * ga.K; }
;   f32x4 acc[2][2][4][2] = {};
;   bf16x8 At[4][2], B0[2][2], B1[2][2];
;   int nt = ga.K / BK;
;   asm volatile("s_waitcnt vmcnt(0)" ::: "memory");
;   __syncthreads();
;   if (!prefetched) {
;     STAGE(SB(0, 0), Bt, ldb, bcol, 0); STAGE(SA(0, 0), A, lda, brow, 0);
;     STAGE(SB(0, 1), Bt, ldb, bcol + HALF, 0); STAGE(SA(0, 1), A, lda, brow + HALF, 0);
;   }
;   if (wr == 1) BAR;
;   WAIT_V(4); BAR;
;   if (!prefetched) { STAGE(SB(1, 0), Bt, ldb, bcol, 1); STAGE(SA(1, 0), A, lda, brow, 1); STAGE(SB(1, 1), Bt, ldb, bcol + HALF, 1); }
;   WAIT_V(6); BAR;
.LBB0_502:
	s_waitcnt lgkmcnt(0)
	v_mbcnt_lo_u32_b32 v4, -1, 0
	v_mbcnt_hi_u32_b32 v4, -1, v4
	v_readlane_b32 s2, v254, 38
	v_or_b32_e32 v149, s60, v4
	v_bfe_i32 v1, v149, 27, 1
	v_lshlrev_b32_e32 v7, 4, v149
	v_lshrrev_b32_e32 v1, 22, v1
	s_mov_b32 s12, s2
	s_ashr_i32 s2, s62, 31
	v_add_u32_e32 v1, v7, v1
	s_lshr_b32 s2, s2, 29
	v_and_b32_e32 v1, 0xfffffc00, v1
	v_readlane_b32 s3, v254, 39
	s_add_i32 s2, s62, s2
	v_sub_u32_e32 v1, v7, v1
	s_ashr_i32 s3, s2, 3
	s_and_b32 s2, s2, -8
	v_ashrrev_i32_e32 v0, 31, v149
	v_lshrrev_b32_e32 v2, 4, v1
	s_sub_i32 s2, s62, s2
	v_lshrrev_b32_e32 v0, 26, v0
	v_bitop3_b32 v1, v2, v1, 32 bitop3:0x6c
	s_lshr_b32 s6, s2, 31
	v_add_u32_e32 v0, v149, v0
	v_ashrrev_i32_e32 v3, 31, v1
	s_or_b32 s6, s57, s6
	v_ashrrev_i32_e32 v0, 6, v0
	v_lshrrev_b32_e32 v3, 26, v3
	s_mul_i32 s2, s2, s6
	v_lshlrev_b32_e32 v2, 3, v0
	v_add_u32_e32 v3, v1, v3
	s_add_i32 s2, s2, s3
	v_and_b32_e32 v2, 0x7ffffff0, v2
	v_ashrrev_i32_e32 v5, 6, v3
	s_abs_i32 s6, s2
	v_readlane_b32 s7, v254, 53
	v_add_u32_e32 v5, v5, v2
	v_and_b32_e32 v2, 0xc0, v3
	s_mul_hi_u32 s7, s6, s7
	v_sub_u32_e32 v1, v1, v2
	v_add_u32_e32 v2, 0x2000, v7
	s_mul_i32 s8, s7, s10
	v_ashrrev_i32_e32 v3, 31, v2
	s_sub_i32 s6, s6, s8
	v_lshrrev_b32_e32 v3, 22, v3
	s_ashr_i32 s3, s2, 31
	s_add_i32 s8, s7, 1
	s_sub_i32 s9, s6, s10
	v_add_u32_e32 v3, v2, v3
	s_cmp_ge_u32 s6, s10
	v_ashrrev_i32_e32 v3, 10, v3
	s_cselect_b32 s7, s8, s7
	v_mul_i32_i24_e32 v8, 0x400, v3
	s_cselect_b32 s6, s9, s6
	s_add_i32 s8, s7, 1
	v_sub_u32_e32 v2, v2, v8
	s_cmp_ge_u32 s6, s10
	v_lshrrev_b32_e32 v8, 4, v2
	s_cselect_b32 s6, s8, s7
	v_bitop3_b32 v8, v8, v2, 32 bitop3:0x6c
	s_xor_b32 s6, s6, s3
	v_ashrrev_i32_e32 v9, 31, v8
	s_sub_i32 s3, s6, s3
	v_lshrrev_b32_e32 v9, 26, v9
	s_lshl_b32 s6, s3, 3
	v_lshlrev_b32_e32 v2, 3, v3
	v_add_u32_e32 v9, v8, v9
	s_sub_i32 s7, 32, s6
	v_and_b32_e32 v2, 0x7ffffff0, v2
	v_ashrrev_i32_e32 v10, 6, v9
	s_min_i32 s7, s7, 8
	v_add_u32_e32 v10, v10, v2
	v_lshlrev_b32_e32 v2, 5, v3
	v_and_b32_e32 v3, 0xc0, v9
	s_abs_i32 s8, s7
	v_lshlrev_b32_e32 v0, 5, v0
	v_ashrrev_i16_sdwa v1, v177, sext(v1) dst_sel:DWORD dst_unused:UNUSED_PAD src0_sel:DWORD src1_sel:BYTE_0
	v_sub_u32_e32 v3, v8, v3
	v_cvt_f32_u32_e32 v9, s8
	v_and_b32_e32 v0, 32, v0
	v_bfe_i32 v1, v1, 0, 16
	v_ashrrev_i16_sdwa v3, v177, sext(v3) dst_sel:DWORD dst_unused:UNUSED_PAD src0_sel:DWORD src1_sel:BYTE_0
	v_add_u32_e32 v6, v0, v1
	v_and_b32_e32 v2, 32, v2
	v_bfe_i32 v3, v3, 0, 16
	v_mul_lo_u32 v5, v5, s12
	v_add_u32_e32 v8, v2, v3
	v_add_lshl_u32 v128, v6, v5, 1
	v_mul_lo_u32 v6, v10, s12
	v_add_lshl_u32 v166, v8, v6, 1
	v_rcp_iflag_f32_e32 v8, v9
	s_sub_i32 s12, 0, s8
	s_mul_i32 s3, s3, s10
	s_sub_i32 s2, s2, s3
	v_mul_f32_e32 v8, 0x4f7ffffe, v8
	v_cvt_u32_f32_e32 v8, v8
	s_abs_i32 s9, s2
	s_xor_b32 s3, s2, s7
	s_ashr_i32 s3, s3, 31
	v_readfirstlane_b32 s13, v8
	s_mul_i32 s12, s12, s13
	s_mul_hi_u32 s12, s13, s12
	s_add_i32 s13, s13, s12
	s_mul_hi_u32 s12, s9, s13
	s_mul_i32 s13, s12, s8
	s_sub_i32 s9, s9, s13
	s_add_i32 s13, s12, 1
	s_sub_i32 s14, s9, s8
	s_cmp_ge_u32 s9, s8
	s_cselect_b32 s12, s13, s12
	s_cselect_b32 s9, s14, s9
	s_add_i32 s13, s12, 1
	s_cmp_ge_u32 s9, s8
	s_cselect_b32 s8, s13, s12
	s_xor_b32 s8, s8, s3
	s_sub_i32 s3, s8, s3
	s_mul_i32 s7, s3, s7
	s_sub_i32 s2, s2, s7
	s_add_i32 s2, s2, s6
	s_ashr_i32 s87, s3, s34
	s_lshl_b32 s6, s2, 8
	s_and_b32 s7, s3, 3
	s_lshl_b32 s12, s87, 8
	s_cmp_gt_i32 s87, 19
	v_readlane_b32 s8, v254, 36
	s_cselect_b64 s[2:3], -1, 0
	v_readlane_b32 s9, v254, 37
	s_and_b64 s[2:3], s[8:9], s[2:3]
	s_and_b64 s[2:3], s[2:3], exec
	s_cselect_b32 s2, 0x100, 0
	s_lshl_b32 s13, s2, 1
	v_readlane_b32 s2, v254, 30
	v_readlane_b32 s3, v254, 31
	s_add_u32 s8, s2, s13
	s_addc_u32 s9, s3, 0
	s_add_u32 s16, s88, s13
	s_addc_u32 s17, s89, 0
	v_mov_b32_e32 v8, s35
	v_mul_u32_u24_e32 v8, s7, v8
	s_and_b64 s[2:3], s[90:91], exec
	v_readfirstlane_b32 s2, v8
	s_cselect_b32 s2, 0, s2
	s_lshl_b32 s84, s2, 1
	s_add_u32 s14, s8, s84
	s_addc_u32 s15, s9, 0
	v_readlane_b32 s2, v254, 54
	s_add_u32 s8, s16, s84
	v_readlane_b32 s3, v254, 55
	s_addc_u32 s9, s17, 0
	s_cmp_eq_u32 s101, 0x53574947
	s_cselect_b32 s101, 1, 0
	v_readlane_b32 s100, v254, 54
	s_nop 3
	s_cmp_lg_u32 s100, 0
	s_cselect_b32 s100, 1, 0
	s_and_b32 s101, s101, s100
	s_cbranch_scc1 .Lth_w1s
	s_waitcnt vmcnt(0)
	s_branch .Lth_w1d
.Lth_w1s:
	s_waitcnt vmcnt(24)
.Lth_w1d:
	s_and_b64 vcc, exec, s[2:3]
	v_readlane_b32 s2, v253, 22
	v_add_u32_e32 v150, 0, v7
	s_mul_hi_i32 s17, s12, s11
	v_add_u32_e32 v152, s2, v7
	v_readlane_b32 s2, v253, 23
	s_mul_i32 s18, s12, s11
	v_add_u32_e32 v151, 0x2000, v150
	v_add_u32_e32 v148, s2, v7
	v_add_u32_e32 v147, 0x4000, v150
	v_add_u32_e32 v146, 0x6000, v150
	s_waitcnt lgkmcnt(0)
	s_barrier
	s_cbranch_vccnz .LBB0_504
	s_add_u32 s2, s14, s18
	v_readfirstlane_b32 s16, v152
	v_add_u32_e32 v8, 0x2000, v152
	s_addc_u32 s3, s15, s17
	s_mov_b32 m0, s16
	v_readfirstlane_b32 s16, v8
	global_load_lds_dwordx4 v128, s[2:3]
	s_mov_b32 m0, s16
	v_readfirstlane_b32 s16, v150
	global_load_lds_dwordx4 v166, s[2:3]
	s_mul_i32 s2, s6, s11
	s_mul_hi_i32 s3, s6, s11
	s_add_u32 s2, s8, s2
	s_addc_u32 s3, s9, s3
	s_mov_b32 m0, s16
	v_readfirstlane_b32 s16, v151
	global_load_lds_dwordx4 v128, s[2:3]
	s_mov_b32 m0, s16
	v_readfirstlane_b32 s16, v148
	global_load_lds_dwordx4 v166, s[2:3]
	s_or_b32 s2, s12, 0x80
	s_mul_hi_i32 s3, s2, s11
	s_mul_i32 s2, s2, s11
	s_add_u32 s2, s14, s2
	v_add_u32_e32 v8, 0x2000, v148
	s_addc_u32 s3, s15, s3
	s_mov_b32 m0, s16
	v_readfirstlane_b32 s16, v8
	global_load_lds_dwordx4 v128, s[2:3]
	s_mov_b32 m0, s16
	v_readfirstlane_b32 s16, v147
	global_load_lds_dwordx4 v166, s[2:3]
	s_or_b32 s2, s6, 0x80
	s_mul_hi_i32 s3, s2, s11
	s_mul_i32 s2, s2, s11
	s_add_u32 s2, s8, s2
	s_addc_u32 s3, s9, s3
	s_mov_b32 m0, s16
	v_readfirstlane_b32 s16, v146
	global_load_lds_dwordx4 v128, s[2:3]
	s_mov_b32 m0, s16
	s_nop 0
	global_load_lds_dwordx4 v166, s[2:3]

; #define STAGE(P, BASE, LD, br, kt) STAGE_(P, BASE, LD, br, kt, ((&(BASE) == &A) ? aoff0 : boff0), ((&(BASE) == &A) ? aoff1 : boff1))
; #define WAIT_V(n) asm volatile("s_waitcnt vmcnt(" #n ")" ::: "memory")
; #define BAR __builtin_amdgcn_s_barrier()
; __device__ __forceinline__ void gemm_tile(const GemmArgs& ga, int wgid, int next_wgid, bool prefetched, u16* shm, unsigned char* ws, int wv_) {
;     ...
;   {
;     int wid = tid >> 6, lane = tid & 63, wc = wid & 3, fr = lane & 15, fq = lane >> 4;
;     wr = wid >> 2;
;     int pt = (fr * 64 + fq * 16) ^ ((fr >> 3) << 5);
;     pa = (const char*)shm + wr * 8192 + pt;
;     pb = (const char*)shm + 65536 + wc * 4096 + pt;
;   }
;     ...
;   if (wr == 1) BAR;
;   WAIT_V(4); BAR;
;   if (!prefetched) { STAGE(SB(1, 0), Bt, ldb, bcol, 1); STAGE(SA(1, 0), A, lda, brow, 1); STAGE(SB(1, 1), Bt, ldb, bcol + HALF, 1); }
;   WAIT_V(6); BAR;
.LBB0_506:
	s_or_b64 exec, exec, s[2:3]
	v_readlane_b32 s2, v254, 54
	v_readlane_b32 s3, v254, 55
	s_cmp_eq_u32 s101, 1
	s_cbranch_scc1 .Lth_w2d
	s_waitcnt vmcnt(4)
.Lth_w2d:
	s_xor_b64 s[2:3], s[2:3], -1
	s_andn2_b64 vcc, exec, s[2:3]
	v_readlane_b32 s2, v253, 24
	v_readlane_b32 s19, v253, 25
	s_mul_i32 s3, s43, s6
	v_add_u32_e32 v156, s2, v7
	s_mul_hi_u32 s2, s42, s6
	s_mul_i32 s16, s42, s6
	v_add_u32_e32 v155, 0x8000, v150
	v_add_u32_e32 v154, 0xa000, v150
	v_add_u32_e32 v153, s19, v7
	s_barrier
	s_cbranch_vccnz .LBB0_508
	s_add_u32 s18, s14, s18
	s_addc_u32 s19, s15, s17
	v_mov_b32_e32 v129, v167
	v_lshl_add_u64 v[10:11], s[18:19], 0, v[128:129]
	v_readfirstlane_b32 s17, v156
	v_add_u32_e32 v7, 0x2000, v156
	v_lshl_add_u64 v[10:11], v[10:11], 0, s[70:71]
	s_mov_b32 m0, s17
	v_readfirstlane_b32 s17, v7
	global_load_lds_dwordx4 v[10:11], off
	s_mov_b32 m0, s17
	s_ashr_i32 s17, s6, 31
	s_mul_i32 s17, s42, s17
	s_add_i32 s17, s2, s17
	s_add_i32 s17, s17, s3
	v_lshl_add_u64 v[10:11], s[18:19], 0, v[166:167]
	s_add_u32 s18, s8, s16
	v_lshl_add_u64 v[10:11], v[10:11], 0, s[70:71]
	s_addc_u32 s19, s9, s17
	global_load_lds_dwordx4 v[10:11], off
	v_lshl_add_u64 v[10:11], s[18:19], 0, v[128:129]
	v_readfirstlane_b32 s17, v155
	v_lshl_add_u64 v[10:11], v[10:11], 0, s[70:71]
	s_mov_b32 m0, s17
	v_readfirstlane_b32 s17, v154
	global_load_lds_dwordx4 v[10:11], off
	s_mov_b32 m0, s17
	s_or_b32 s17, s12, 0x80
	v_lshl_add_u64 v[10:11], s[18:19], 0, v[166:167]
	s_mul_hi_i32 s18, s17, s11
	s_mul_i32 s17, s17, s11
	s_add_u32 s14, s14, s17
	v_lshl_add_u64 v[10:11], v[10:11], 0, s[70:71]
	s_addc_u32 s15, s15, s18
	global_load_lds_dwordx4 v[10:11], off
	v_lshl_add_u64 v[10:11], s[14:15], 0, v[128:129]
	v_readfirstlane_b32 s17, v153
	v_lshl_add_u64 v[10:11], v[10:11], 0, s[70:71]
	s_mov_b32 m0, s17
	v_add_u32_e32 v7, 0x2000, v153
	global_load_lds_dwordx4 v[10:11], off
	v_lshl_add_u64 v[10:11], s[14:15], 0, v[166:167]
	v_readfirstlane_b32 s14, v7
	v_lshl_add_u64 v[10:11], v[10:11], 0, s[70:71]
	s_mov_b32 m0, s14
	s_nop 0
	global_load_lds_dwordx4 v[10:11], off
.LBB0_508:
	v_and_b32_e32 v7, 15, v4
	v_and_b32_e32 v9, 48, v4
	v_lshlrev_b32_e32 v4, 2, v4
	v_lshlrev_b32_e32 v7, 6, v7
	v_and_b32_e32 v4, 32, v4
	v_bitop3_b32 v158, v7, v4, v9 bitop3:0x36
	v_lshlrev_b32_e32 v4, 13, v8
	v_add3_u32 v157, 0, v4, v158
	v_lshlrev_b32_e32 v4, 6, v149
	s_cmp_eq_u32 s101, 1
	s_cbranch_scc1 .Lth_w3d
	s_waitcnt vmcnt(6)
; #define STAGE(P, BASE, LD, br, kt) STAGE_(P, BASE, LD, br, kt, ((&(BASE) == &A) ? aoff0 : boff0), ((&(BASE) == &A) ? aoff1 : boff1))
; #define LDA(dst, b, h)                                                                     \
;   for (int m = 0; m < 4; ++m)                                                              \
;     for (int k = 0; k < 2; ++k)                                                            \
;   dst[m][k] = *reinterpret_cast<const bf16x8*>(pa + (((b) * 2 + (h)) * 16384 + m * 2048 + k * 1024))
; #define LDB(dst, b, h)                                                                     \
;   for (int n = 0; n < 2; ++n)                                                              \
;     for (int k = 0; k < 2; ++k)                                                            \
;   dst[n][k] = *reinterpret_cast<const bf16x8*>(pb + (((b) * 2 + (h)) * 16384 + n * 2048 + k * 1024))
; #define WAIT_V(n) asm volatile("s_waitcnt vmcnt(" #n ")" ::: "memory")
; #define BAR __builtin_amdgcn_s_barrier()
; #define SCHED __builtin_amdgcn_sched_barrier(0)
; __device__ __forceinline__ void gemm_tile(const GemmArgs& ga, int wgid, int next_wgid, bool prefetched, u16* shm, unsigned char* ws, int wv_) {
;     ...
;   f32x4 acc[2][2][4][2] = {};
;   bf16x8 At[4][2], B0[2][2], B1[2][2];
;   int nt = ga.K / BK;
;   asm volatile("s_waitcnt vmcnt(0)" ::: "memory");
;   __syncthreads();
;   if (!prefetched) {
;     STAGE(SB(0, 0), Bt, ldb, bcol, 0); STAGE(SA(0, 0), A, lda, brow, 0);
;     STAGE(SB(0, 1), Bt, ldb, bcol + HALF, 0); STAGE(SA(0, 1), A, lda, brow + HALF, 0);
;   }
;   if (wr == 1) BAR;
;   WAIT_V(4); BAR;
;   if (!prefetched) { STAGE(SB(1, 0), Bt, ldb, bcol, 1); STAGE(SA(1, 0), A, lda, brow, 1); STAGE(SB(1, 1), Bt, ldb, bcol + HALF, 1); }
;   WAIT_V(6); BAR;
;   for (int t = 0; t < nt - 2; t += 2) {
;     LDB(B0, 0, 0); SCHED; LDA(At, 0, 0); STAGE(SA(1, 1), A, lda, brow + HALF, t + 1);
.Lth_w3d:
	s_mov_b32 s101, 0
	v_and_b32_e32 v4, 0x3000, v4
	v_readlane_b32 s14, v253, 22
	v_mov_b32_e32 v129, v167
	s_and_b64 vcc, exec, s[28:29]
	v_add_u32_e32 v159, s14, v4
	v_readlane_b32 s20, v253, 44
	s_barrier
	v_readlane_b32 s21, v253, 45
	s_cbranch_vccz .LBB0_512
	s_ashr_i32 s17, s12, 31
	s_ashr_i32 s18, s6, 31
	s_add_u32 s14, s12, 0x80
	s_addc_u32 s15, s17, 0
	s_mul_i32 s15, s42, s15
	s_mul_hi_u32 s19, s42, s14
	s_add_i32 s15, s19, s15
	s_mul_i32 s19, s43, s14
	s_add_i32 s15, s15, s19
	s_mul_i32 s14, s42, s14
	s_add_u32 s14, s14, s13
	s_addc_u32 s15, s15, 0
	v_readlane_b32 s22, v254, 30
	v_add_u32_e32 v0, v5, v0
	v_readlane_b32 s23, v254, 31
	s_add_u32 s14, s22, s14
	v_add_u32_e32 v2, v6, v2
	v_add_lshl_u32 v0, v0, v1, 1
	v_mov_b32_e32 v1, v167
	s_addc_u32 s15, s23, s15
	v_add_lshl_u32 v2, v2, v3, 1
	v_mov_b32_e32 v3, v167
	v_lshl_add_u64 v[130:131], s[14:15], 0, v[0:1]
	v_lshl_add_u64 v[132:133], s[14:15], 0, v[2:3]
	s_mul_i32 s14, s42, s18
	s_add_i32 s2, s2, s14
	s_add_i32 s2, s2, s3
	s_add_u32 s3, s16, s13
	s_addc_u32 s14, s2, 0
	s_add_u32 s2, s88, s3
	s_addc_u32 s3, s89, s14
	v_lshl_add_u64 v[134:135], s[2:3], 0, v[0:1]
	v_lshl_add_u64 v[136:137], s[2:3], 0, v[2:3]
	s_mul_hi_u32 s2, s42, s12
	s_mul_i32 s3, s42, s17
	s_add_i32 s2, s2, s3
	s_mul_i32 s3, s43, s12
	s_add_i32 s2, s2, s3
	s_mul_i32 s3, s42, s12
	s_add_u32 s3, s3, s13
	s_addc_u32 s14, s2, 0
	s_add_u32 s2, s22, s3
	s_addc_u32 s3, s23, s14
	v_lshl_add_u64 v[138:139], s[2:3], 0, v[0:1]
	v_lshl_add_u64 v[140:141], s[2:3], 0, v[2:3]
	s_add_u32 s2, s6, 0x80
	s_addc_u32 s3, s18, 0
	s_mul_i32 s3, s42, s3
	s_mul_hi_u32 s14, s42, s2
	s_add_i32 s3, s14, s3
	s_mul_i32 s14, s43, s2
	s_add_i32 s3, s3, s14
	s_mul_i32 s2, s42, s2
	s_add_u32 s2, s2, s13
	s_addc_u32 s3, s3, 0
	s_add_u32 s2, s88, s2
	s_addc_u32 s3, s89, s3
	v_lshl_add_u64 v[142:143], s[2:3], 0, v[0:1]
	v_mov_b32_e32 v0, 0
	v_lshl_add_u64 v[144:145], s[2:3], 0, v[2:3]
	s_mov_b32 s2, 0
	v_mov_b32_e32 v1, v0
	v_mov_b32_e32 v2, v0
	v_mov_b32_e32 v3, v0
	v_mov_b32_e32 v4, v0
	v_mov_b32_e32 v5, v0
	v_mov_b32_e32 v6, v0
	v_mov_b32_e32 v7, v0
	v_mov_b32_e32 v16, v0
	v_mov_b32_e32 v17, v0
	v_mov_b32_e32 v18, v0
	v_mov_b32_e32 v19, v0
	v_mov_b32_e32 v28, v0
	v_mov_b32_e32 v29, v0
	v_mov_b32_e32 v30, v0
	v_mov_b32_e32 v31, v0
	v_mov_b32_e32 v40, v0
	v_mov_b32_e32 v41, v0
	v_mov_b32_e32 v42, v0
	v_mov_b32_e32 v43, v0
	v_mov_b32_e32 v52, v0
	v_mov_b32_e32 v53, v0
	v_mov_b32_e32 v54, v0
	v_mov_b32_e32 v55, v0
	v_mov_b32_e32 v64, v0
	v_mov_b32_e32 v65, v0
	v_mov_b32_e32 v66, v0
	v_mov_b32_e32 v67, v0
	v_mov_b32_e32 v76, v0
	v_mov_b32_e32 v77, v0
	v_mov_b32_e32 v78, v0
	v_mov_b32_e32 v79, v0
	v_mov_b32_e32 v8, v0
	v_mov_b32_e32 v9, v0
	v_mov_b32_e32 v10, v0
	v_mov_b32_e32 v11, v0
	v_mov_b32_e32 v20, v0
	v_mov_b32_e32 v21, v0
	v_mov_b32_e32 v22, v0
	v_mov_b32_e32 v23, v0
	v_mov_b32_e32 v32, v0
	v_mov_b32_e32 v33, v0
	v_mov_b32_e32 v34, v0
	v_mov_b32_e32 v35, v0
	v_mov_b32_e32 v44, v0
	v_mov_b32_e32 v45, v0
	v_mov_b32_e32 v46, v0
	v_mov_b32_e32 v47, v0
	v_mov_b32_e32 v56, v0
	v_mov_b32_e32 v57, v0
	v_mov_b32_e32 v58, v0
	v_mov_b32_e32 v59, v0
	v_mov_b32_e32 v68, v0
	v_mov_b32_e32 v69, v0
	v_mov_b32_e32 v70, v0
	v_mov_b32_e32 v71, v0
	v_mov_b32_e32 v80, v0
	v_mov_b32_e32 v81, v0
	v_mov_b32_e32 v82, v0
	v_mov_b32_e32 v83, v0
	v_mov_b32_e32 v92, v0
	v_mov_b32_e32 v93, v0
	v_mov_b32_e32 v94, v0
	v_mov_b32_e32 v95, v0
	v_mov_b32_e32 v12, v0
	v_mov_b32_e32 v13, v0
	v_mov_b32_e32 v14, v0
	v_mov_b32_e32 v15, v0
	v_mov_b32_e32 v24, v0
	v_mov_b32_e32 v25, v0
	v_mov_b32_e32 v26, v0
	v_mov_b32_e32 v27, v0
	v_mov_b32_e32 v36, v0
	v_mov_b32_e32 v37, v0
	v_mov_b32_e32 v38, v0
	v_mov_b32_e32 v39, v0
	v_mov_b32_e32 v48, v0
	v_mov_b32_e32 v49, v0
	v_mov_b32_e32 v50, v0
	v_mov_b32_e32 v51, v0
	v_mov_b32_e32 v60, v0
	v_mov_b32_e32 v61, v0
	v_mov_b32_e32 v62, v0
	v_mov_b32_e32 v63, v0
	v_mov_b32_e32 v72, v0
	v_mov_b32_e32 v73, v0
	v_mov_b32_e32 v74, v0
	v_mov_b32_e32 v75, v0
	v_mov_b32_e32 v84, v0
	v_mov_b32_e32 v85, v0
	v_mov_b32_e32 v86, v0
	v_mov_b32_e32 v87, v0
	v_mov_b32_e32 v96, v0
	v_mov_b32_e32 v97, v0
	v_mov_b32_e32 v98, v0
	v_mov_b32_e32 v99, v0
	v_mov_b32_e32 v88, v0
	v_mov_b32_e32 v89, v0
	v_mov_b32_e32 v90, v0
	v_mov_b32_e32 v91, v0
	v_mov_b32_e32 v100, v0
	v_mov_b32_e32 v101, v0
	v_mov_b32_e32 v102, v0
	v_mov_b32_e32 v103, v0
	v_mov_b32_e32 v104, v0
	v_mov_b32_e32 v105, v0
	v_mov_b32_e32 v106, v0
	v_mov_b32_e32 v107, v0
	v_mov_b32_e32 v108, v0
	v_mov_b32_e32 v109, v0
	v_mov_b32_e32 v110, v0
	v_mov_b32_e32 v111, v0
	v_mov_b32_e32 v112, v0
	v_mov_b32_e32 v113, v0
	v_mov_b32_e32 v114, v0
	v_mov_b32_e32 v115, v0
	v_mov_b32_e32 v116, v0
	v_mov_b32_e32 v117, v0
	v_mov_b32_e32 v118, v0
	v_mov_b32_e32 v119, v0
	v_mov_b32_e32 v120, v0
	v_mov_b32_e32 v121, v0
	v_mov_b32_e32 v122, v0
	v_mov_b32_e32 v123, v0
	v_mov_b32_e32 v124, v0
	v_mov_b32_e32 v125, v0
	v_mov_b32_e32 v126, v0
	v_mov_b32_e32 v127, v0

; __device__ __forceinline__ u32 pack2(float a, float b) { return (u32)f2bf(a) | ((u32)f2bf(b) << 16); }
; __device__ __forceinline__ float sigmoidf_(float x) { return __builtin_amdgcn_rcpf(1.f + __expf(-x)); }
; __device__ __forceinline__ void gemm_tile(const GemmArgs& ga, int wgid, int next_wgid, bool prefetched, u16* shm, unsigned char* ws, int wv_) {
;     ...
;   if (epi == EPI_SWIGLU) {
;     const int oc = pn * HALF + (wc * 16 + fr) * 2;
;     float sc[2][4][4];
;     _Pragma("unroll") for (int ai = 0; ai < 2; ++ai)
;       _Pragma("unroll") for (int m = 0; m < 4; ++m)
;         _Pragma("unroll") for (int j = 0; j < 4; ++j) sc[ai][m][j] = e_ss[rbase + ai * HALF + m * 16 + j];
;     _Pragma("unroll") for (int ai = 0; ai < 2; ++ai)
;       _Pragma("unroll") for (int m = 0; m < 4; ++m)
;         _Pragma("unroll") for (int j = 0; j < 4; ++j) {
;           int row = rbase + ai * HALF + m * 16 + j;
;           float s = rsqrtf(sc[ai][m][j] * (1.f / D_) + 1e-6f);
;           float h2[2];
;           _Pragma("unroll") for (int n = 0; n < 2; ++n) {
;             float a1 = acc[ai][0][m][n][j] * s, a3 = acc[ai][1][m][n][j] * s;
;             h2[n] = a1 * sigmoidf_(a1) * a3;
;           }
;           *(u32*)(e_outb + (size_t)row * F_ + oc) = pack2(h2[0], h2[1]);
;         }
.Lsswd_s:
	v_mov_b64_e32 v[0:1], v[208:209]
	v_mov_b64_e32 v[2:3], v[210:211]
	v_pk_fma_f32 v[0:1], v[0:1], s[12:13], v[130:131] op_sel_hi:[1,0,0]
	s_nop 0
	v_pk_fma_f32 v[2:3], v[2:3], s[12:13], v[130:131] op_sel_hi:[1,0,0]
	v_rsq_f32_e32 v0, v0
	s_nop 0
	v_mul_f32_e32 v16, v116, v0
	v_mul_f32_e32 v18, 0xbfb8aa3b, v16
	v_exp_f32_e32 v18, v18
	v_mul_f32_e32 v17, v124, v0
	v_add_f32_e32 v18, 1.0, v18
	v_rcp_f32_e32 v18, v18
	s_nop 0
	v_mul_f32_e32 v16, v16, v18
	v_mul_f32_e32 v16, v17, v16
	v_mul_f32_e32 v17, v112, v0
	v_mul_f32_e32 v18, 0xbfb8aa3b, v17
	v_exp_f32_e32 v18, v18
	v_mul_f32_e32 v0, v120, v0
	v_add_f32_e32 v18, 1.0, v18
	v_rcp_f32_e32 v18, v18
	s_nop 0
	v_mul_f32_e32 v17, v17, v18
	v_mul_f32_e32 v0, v0, v17
	v_cvt_pk_bf16_f32 v0, v16, v0
	global_store_dword v[134:135], v0, off
	v_rsq_f32_e32 v0, v1
	s_nop 0
	v_mul_f32_e32 v1, v117, v0
	v_mul_f32_e32 v17, 0xbfb8aa3b, v1
	v_exp_f32_e32 v17, v17
	v_mul_f32_e32 v16, v125, v0
	v_mad_i64_i32 v[116:117], s[2:3], v11, s8, v[128:129]
	v_add_f32_e32 v17, 1.0, v17
	v_rcp_f32_e32 v17, v17
	s_nop 0
	v_mul_f32_e32 v1, v1, v17
	v_mul_f32_e32 v1, v16, v1
	v_mul_f32_e32 v16, v113, v0
	v_mul_f32_e32 v17, 0xbfb8aa3b, v16
	v_exp_f32_e32 v17, v17
	v_mul_f32_e32 v0, v121, v0
	v_add_f32_e32 v17, 1.0, v17
	v_rcp_f32_e32 v17, v17
	s_nop 0
	v_mul_f32_e32 v16, v16, v17
	v_mul_f32_e32 v0, v0, v16
	v_cvt_pk_bf16_f32 v16, v1, v0
	v_mad_i64_i32 v[0:1], s[2:3], v8, s8, v[128:129]
	v_rsq_f32_e32 v2, v2
	global_store_dword v[0:1], v16, off
	v_mad_i64_i32 v[0:1], s[2:3], v9, s8, v[128:129]
	v_mul_f32_e32 v8, v118, v2
	v_mul_f32_e32 v16, 0xbfb8aa3b, v8
	v_exp_f32_e32 v16, v16
	v_mul_f32_e32 v9, v126, v2
	v_add_f32_e32 v16, 1.0, v16
	v_rcp_f32_e32 v16, v16
	s_nop 0
	v_mul_f32_e32 v8, v8, v16
	v_mul_f32_e32 v8, v9, v8
	v_mul_f32_e32 v9, v114, v2
	v_mul_f32_e32 v16, 0xbfb8aa3b, v9
	v_exp_f32_e32 v16, v16
	v_mul_f32_e32 v2, v122, v2
	v_add_f32_e32 v16, 1.0, v16
	v_rcp_f32_e32 v16, v16
	s_nop 0
	v_mul_f32_e32 v9, v9, v16
	v_mul_f32_e32 v2, v2, v9
	v_cvt_pk_bf16_f32 v2, v8, v2
	global_store_dword v[0:1], v2, off
	v_rsq_f32_e32 v0, v3
	v_mov_b64_e32 v[16:17], v[236:237]
	v_mov_b64_e32 v[18:19], v[238:239]
	v_mul_f32_e32 v1, v119, v0
	v_mul_f32_e32 v3, 0xbfb8aa3b, v1
	v_exp_f32_e32 v3, v3
	v_mul_f32_e32 v2, v127, v0
	v_add_f32_e32 v3, 1.0, v3
	v_rcp_f32_e32 v3, v3
	s_nop 0
	v_mul_f32_e32 v1, v1, v3
	v_mul_f32_e32 v1, v2, v1
	v_mul_f32_e32 v2, v115, v0
	v_mov_b64_e32 v[112:113], v[212:213]
	v_mov_b64_e32 v[114:115], v[214:215]
	v_mul_f32_e32 v3, 0xbfb8aa3b, v2
	v_exp_f32_e32 v3, v3
	v_mul_f32_e32 v0, v123, v0
	v_add_f32_e32 v3, 1.0, v3
	v_rcp_f32_e32 v3, v3
	s_nop 0
	v_mul_f32_e32 v2, v2, v3
	v_mul_f32_e32 v0, v0, v2
	v_cvt_pk_bf16_f32 v2, v1, v0
	v_mad_i64_i32 v[0:1], s[2:3], v10, s8, v[128:129]
	global_store_dword v[0:1], v2, off
	v_pk_fma_f32 v[0:1], v[112:113], s[12:13], v[130:131] op_sel_hi:[1,0,0]
	s_nop 0
	s_nop 0
	v_rsq_f32_e32 v0, v0
	s_nop 0
	v_mul_f32_e32 v2, v100, v0
	v_mul_f32_e32 v8, 0xbfb8aa3b, v2
	v_exp_f32_e32 v8, v8
	v_mul_f32_e32 v3, v108, v0
	v_add_f32_e32 v8, 1.0, v8
	v_rcp_f32_e32 v8, v8
	s_nop 0
	v_mul_f32_e32 v2, v2, v8
	v_mul_f32_e32 v2, v3, v2
	v_mul_f32_e32 v3, v96, v0
	v_mul_f32_e32 v8, 0xbfb8aa3b, v3
	v_exp_f32_e32 v8, v8
	v_mul_f32_e32 v0, v104, v0
	v_add_f32_e32 v8, 1.0, v8
	v_rcp_f32_e32 v8, v8
	s_nop 0
	v_mul_f32_e32 v3, v3, v8
	v_mul_f32_e32 v0, v0, v3
	v_cvt_pk_bf16_f32 v0, v2, v0
	global_store_dword v[116:117], v0, off
	v_rsq_f32_e32 v0, v1
	s_nop 0
	v_mul_f32_e32 v1, v101, v0
	v_mul_f32_e32 v3, 0xbfb8aa3b, v1
	v_exp_f32_e32 v3, v3
	v_mul_f32_e32 v2, v109, v0
	v_add_f32_e32 v3, 1.0, v3
	v_rcp_f32_e32 v3, v3
	s_nop 0
	v_mul_f32_e32 v1, v1, v3
	v_mul_f32_e32 v1, v2, v1
	v_mul_f32_e32 v2, v97, v0
	v_mul_f32_e32 v3, 0xbfb8aa3b, v2
	v_exp_f32_e32 v3, v3
	v_mul_f32_e32 v0, v105, v0
	v_mad_i64_i32 v[96:97], s[2:3], v159, s8, v[128:129]
	v_add_f32_e32 v3, 1.0, v3
	v_rcp_f32_e32 v3, v3
	s_nop 0
	v_mul_f32_e32 v2, v2, v3
	v_mul_f32_e32 v0, v0, v2
	v_cvt_pk_bf16_f32 v2, v1, v0
	v_mad_i64_i32 v[0:1], s[2:3], v162, s8, v[128:129]
	global_store_dword v[0:1], v2, off
	v_pk_fma_f32 v[2:3], v[114:115], s[12:13], v[130:131] op_sel_hi:[1,0,0]
	v_mad_i64_i32 v[0:1], s[2:3], v161, s8, v[128:129]
	s_nop 0
	v_rsq_f32_e32 v2, v2
	s_nop 0
	v_mul_f32_e32 v8, v102, v2
	v_mul_f32_e32 v10, 0xbfb8aa3b, v8
	v_exp_f32_e32 v10, v10
	v_mul_f32_e32 v9, v110, v2
	v_add_f32_e32 v10, 1.0, v10
	v_rcp_f32_e32 v10, v10
	s_nop 0
	v_mul_f32_e32 v8, v8, v10
	v_mul_f32_e32 v8, v9, v8
	v_mul_f32_e32 v9, v98, v2
	v_mul_f32_e32 v10, 0xbfb8aa3b, v9
	v_exp_f32_e32 v10, v10
	v_mul_f32_e32 v2, v106, v2
	v_add_f32_e32 v10, 1.0, v10
	v_rcp_f32_e32 v10, v10
	s_nop 0
	v_mul_f32_e32 v9, v9, v10
	v_mul_f32_e32 v2, v2, v9
	v_cvt_pk_bf16_f32 v2, v8, v2
	global_store_dword v[0:1], v2, off
	v_rsq_f32_e32 v0, v3
	s_nop 0
	v_mul_f32_e32 v1, v103, v0
	v_mul_f32_e32 v3, 0xbfb8aa3b, v1
	v_exp_f32_e32 v3, v3
	v_mul_f32_e32 v2, v111, v0
	v_add_f32_e32 v3, 1.0, v3
	v_rcp_f32_e32 v3, v3
	s_nop 0
	v_mul_f32_e32 v1, v1, v3
	v_mul_f32_e32 v1, v2, v1
	v_mul_f32_e32 v2, v99, v0
	v_mul_f32_e32 v3, 0xbfb8aa3b, v2
	v_exp_f32_e32 v3, v3
	v_mul_f32_e32 v0, v107, v0
	v_add_f32_e32 v3, 1.0, v3
	v_rcp_f32_e32 v3, v3
	s_nop 0
	v_mul_f32_e32 v2, v2, v3
	v_mul_f32_e32 v0, v0, v2
	v_cvt_pk_bf16_f32 v2, v1, v0
	v_mad_i64_i32 v[0:1], s[2:3], v160, s8, v[128:129]
	global_store_dword v[0:1], v2, off
	v_mov_b64_e32 v[0:1], v[216:217]
	v_mov_b64_e32 v[2:3], v[218:219]
	v_pk_fma_f32 v[0:1], v[0:1], s[12:13], v[130:131] op_sel_hi:[1,0,0]
	s_nop 0
	v_pk_fma_f32 v[2:3], v[2:3], s[12:13], v[130:131] op_sel_hi:[1,0,0]
	v_rsq_f32_e32 v0, v0
	s_nop 0
	v_mul_f32_e32 v8, v84, v0
; __device__ __forceinline__ u32 pack2(float a, float b) { return (u32)f2bf(a) | ((u32)f2bf(b) << 16); }
; __device__ __forceinline__ float sigmoidf_(float x) { return __builtin_amdgcn_rcpf(1.f + __expf(-x)); }
; __device__ __forceinline__ void gemm_tile(const GemmArgs& ga, int wgid, int next_wgid, bool prefetched, u16* shm, unsigned char* ws, int wv_) {
;     ...
;   if (epi == EPI_SWIGLU) {
;     const int oc = pn * HALF + (wc * 16 + fr) * 2;
;     float sc[2][4][4];
;     _Pragma("unroll") for (int ai = 0; ai < 2; ++ai)
;       _Pragma("unroll") for (int m = 0; m < 4; ++m)
;         _Pragma("unroll") for (int j = 0; j < 4; ++j) sc[ai][m][j] = e_ss[rbase + ai * HALF + m * 16 + j];
;     _Pragma("unroll") for (int ai = 0; ai < 2; ++ai)
;       _Pragma("unroll") for (int m = 0; m < 4; ++m)
;         _Pragma("unroll") for (int j = 0; j < 4; ++j) {
;           int row = rbase + ai * HALF + m * 16 + j;
;           float s = rsqrtf(sc[ai][m][j] * (1.f / D_) + 1e-6f);
;           float h2[2];
;           _Pragma("unroll") for (int n = 0; n < 2; ++n) {
;             float a1 = acc[ai][0][m][n][j] * s, a3 = acc[ai][1][m][n][j] * s;
;             h2[n] = a1 * sigmoidf_(a1) * a3;
;           }
;           *(u32*)(e_outb + (size_t)row * F_ + oc) = pack2(h2[0], h2[1]);
;         }
	v_mul_f32_e32 v10, 0xbfb8aa3b, v8
	v_exp_f32_e32 v10, v10
	v_mul_f32_e32 v9, v92, v0
	v_add_f32_e32 v10, 1.0, v10
	v_rcp_f32_e32 v10, v10
	s_nop 0
	v_mul_f32_e32 v8, v8, v10
	v_mul_f32_e32 v8, v9, v8
	v_mul_f32_e32 v9, v80, v0
	v_mul_f32_e32 v10, 0xbfb8aa3b, v9
	v_exp_f32_e32 v10, v10
	v_mul_f32_e32 v0, v88, v0
	v_add_f32_e32 v10, 1.0, v10
	v_rcp_f32_e32 v10, v10
	s_nop 0
	v_mul_f32_e32 v9, v9, v10
	v_mul_f32_e32 v0, v0, v9
	v_cvt_pk_bf16_f32 v0, v8, v0
	global_store_dword v[96:97], v0, off
	v_rsq_f32_e32 v0, v1
	s_nop 0
	v_mul_f32_e32 v1, v85, v0
	v_mul_f32_e32 v9, 0xbfb8aa3b, v1
	v_exp_f32_e32 v9, v9
	v_mul_f32_e32 v8, v93, v0
	v_mad_i64_i32 v[84:85], s[2:3], v155, s8, v[128:129]
	v_add_f32_e32 v9, 1.0, v9
	v_rcp_f32_e32 v9, v9
	s_nop 0
	v_mul_f32_e32 v1, v1, v9
	v_mul_f32_e32 v1, v8, v1
	v_mul_f32_e32 v8, v81, v0
	v_mul_f32_e32 v9, 0xbfb8aa3b, v8
	v_exp_f32_e32 v9, v9
	v_mul_f32_e32 v0, v89, v0
	v_add_f32_e32 v9, 1.0, v9
	v_rcp_f32_e32 v9, v9
	s_nop 0
	v_mul_f32_e32 v8, v8, v9
	v_mul_f32_e32 v0, v0, v8
	v_cvt_pk_bf16_f32 v8, v1, v0
	v_mad_i64_i32 v[0:1], s[2:3], v158, s8, v[128:129]
	global_store_dword v[0:1], v8, off
	v_rsq_f32_e32 v2, v2
	v_mad_i64_i32 v[0:1], s[2:3], v157, s8, v[128:129]
	v_mul_f32_e32 v8, v86, v2
	v_mul_f32_e32 v10, 0xbfb8aa3b, v8
	v_exp_f32_e32 v10, v10
	v_mul_f32_e32 v9, v94, v2
	v_add_f32_e32 v10, 1.0, v10
	v_rcp_f32_e32 v10, v10
	s_nop 0
	v_mul_f32_e32 v8, v8, v10
	v_mul_f32_e32 v8, v9, v8
	v_mul_f32_e32 v9, v82, v2
	v_mul_f32_e32 v10, 0xbfb8aa3b, v9
	v_exp_f32_e32 v10, v10
	v_mul_f32_e32 v2, v90, v2
	v_add_f32_e32 v10, 1.0, v10
	v_rcp_f32_e32 v10, v10
	s_nop 0
	v_mul_f32_e32 v9, v9, v10
	v_mul_f32_e32 v2, v2, v9
	v_cvt_pk_bf16_f32 v2, v8, v2
	global_store_dword v[0:1], v2, off
	v_rsq_f32_e32 v0, v3
	s_nop 0
	v_mul_f32_e32 v1, v87, v0
	v_mul_f32_e32 v3, 0xbfb8aa3b, v1
	v_exp_f32_e32 v3, v3
	v_mul_f32_e32 v2, v95, v0
	v_add_f32_e32 v3, 1.0, v3
	v_rcp_f32_e32 v3, v3
	s_nop 0
	v_mul_f32_e32 v1, v1, v3
	v_mul_f32_e32 v1, v2, v1
	v_mul_f32_e32 v2, v83, v0
	v_mov_b64_e32 v[80:81], v[220:221]
	v_mov_b64_e32 v[82:83], v[222:223]
	v_mul_f32_e32 v3, 0xbfb8aa3b, v2
	v_exp_f32_e32 v3, v3
	v_mul_f32_e32 v0, v91, v0
	v_add_f32_e32 v3, 1.0, v3
	v_rcp_f32_e32 v3, v3
	s_nop 0
	v_mul_f32_e32 v2, v2, v3
	v_mul_f32_e32 v0, v0, v2
	v_cvt_pk_bf16_f32 v2, v1, v0
	v_mad_i64_i32 v[0:1], s[2:3], v156, s8, v[128:129]
	global_store_dword v[0:1], v2, off
	v_pk_fma_f32 v[0:1], v[80:81], s[12:13], v[130:131] op_sel_hi:[1,0,0]
	s_nop 0
	s_nop 0
	v_rsq_f32_e32 v0, v0
	s_nop 0
	v_mul_f32_e32 v2, v68, v0
	v_mul_f32_e32 v8, 0xbfb8aa3b, v2
	v_exp_f32_e32 v8, v8
	v_mul_f32_e32 v3, v76, v0
	v_add_f32_e32 v8, 1.0, v8
	v_rcp_f32_e32 v8, v8
	s_nop 0
	v_mul_f32_e32 v2, v2, v8
	v_mul_f32_e32 v2, v3, v2
	v_mul_f32_e32 v3, v64, v0
	v_mul_f32_e32 v8, 0xbfb8aa3b, v3
	v_exp_f32_e32 v8, v8
	v_mul_f32_e32 v0, v72, v0
	v_add_f32_e32 v8, 1.0, v8
	v_rcp_f32_e32 v8, v8
	s_nop 0
	v_mul_f32_e32 v3, v3, v8
	v_mul_f32_e32 v0, v0, v3
	v_cvt_pk_bf16_f32 v0, v2, v0
	global_store_dword v[84:85], v0, off
	v_rsq_f32_e32 v0, v1
	s_nop 0
	v_mul_f32_e32 v1, v69, v0
	v_mul_f32_e32 v3, 0xbfb8aa3b, v1
	v_exp_f32_e32 v3, v3
	v_mul_f32_e32 v2, v77, v0
	v_add_f32_e32 v3, 1.0, v3
	v_rcp_f32_e32 v3, v3
	s_nop 0
	v_mul_f32_e32 v1, v1, v3
	v_mul_f32_e32 v1, v2, v1
	v_mul_f32_e32 v2, v65, v0
	v_mul_f32_e32 v3, 0xbfb8aa3b, v2
	v_exp_f32_e32 v3, v3
	v_mul_f32_e32 v0, v73, v0
	v_mad_i64_i32 v[64:65], s[2:3], v151, s8, v[128:129]
	v_add_f32_e32 v3, 1.0, v3
	v_rcp_f32_e32 v3, v3
	s_nop 0
	v_mul_f32_e32 v2, v2, v3
	v_mul_f32_e32 v0, v0, v2
	v_cvt_pk_bf16_f32 v2, v1, v0
	v_mad_i64_i32 v[0:1], s[2:3], v154, s8, v[128:129]
	global_store_dword v[0:1], v2, off
	v_pk_fma_f32 v[2:3], v[82:83], s[12:13], v[130:131] op_sel_hi:[1,0,0]
	v_mad_i64_i32 v[0:1], s[2:3], v153, s8, v[128:129]
	s_nop 0
	v_rsq_f32_e32 v2, v2
	s_nop 0
	v_mul_f32_e32 v8, v70, v2
	v_mul_f32_e32 v10, 0xbfb8aa3b, v8
	v_exp_f32_e32 v10, v10
	v_mul_f32_e32 v9, v78, v2
	v_add_f32_e32 v10, 1.0, v10
	v_rcp_f32_e32 v10, v10
	s_nop 0
	v_mul_f32_e32 v8, v8, v10
	v_mul_f32_e32 v8, v9, v8
	v_mul_f32_e32 v9, v66, v2
	v_mul_f32_e32 v10, 0xbfb8aa3b, v9
	v_exp_f32_e32 v10, v10
	v_mul_f32_e32 v2, v74, v2
	v_add_f32_e32 v10, 1.0, v10
	v_rcp_f32_e32 v10, v10
	s_nop 0
	v_mul_f32_e32 v9, v9, v10
	v_mul_f32_e32 v2, v2, v9
	v_cvt_pk_bf16_f32 v2, v8, v2
	global_store_dword v[0:1], v2, off
	v_rsq_f32_e32 v0, v3
	s_nop 0
	v_mul_f32_e32 v1, v71, v0
	v_mul_f32_e32 v3, 0xbfb8aa3b, v1
	v_exp_f32_e32 v3, v3
	v_mul_f32_e32 v2, v79, v0
	v_add_f32_e32 v3, 1.0, v3
	v_rcp_f32_e32 v3, v3
	s_nop 0
	v_mul_f32_e32 v1, v1, v3
	v_mul_f32_e32 v1, v2, v1
	v_mul_f32_e32 v2, v67, v0
	v_mul_f32_e32 v3, 0xbfb8aa3b, v2
	v_exp_f32_e32 v3, v3
	v_mul_f32_e32 v0, v75, v0
	v_add_f32_e32 v3, 1.0, v3
	v_rcp_f32_e32 v3, v3
	s_nop 0
	v_mul_f32_e32 v2, v2, v3
	v_mul_f32_e32 v0, v0, v2
	v_cvt_pk_bf16_f32 v2, v1, v0
	v_mad_i64_i32 v[0:1], s[2:3], v152, s8, v[128:129]
	global_store_dword v[0:1], v2, off
	v_mov_b64_e32 v[0:1], v[224:225]
	v_mov_b64_e32 v[2:3], v[226:227]
	v_pk_fma_f32 v[0:1], v[0:1], s[12:13], v[130:131] op_sel_hi:[1,0,0]
	s_nop 0
	v_pk_fma_f32 v[2:3], v[2:3], s[12:13], v[130:131] op_sel_hi:[1,0,0]
	v_rsq_f32_e32 v0, v0
	s_nop 0
	v_mul_f32_e32 v8, v52, v0
	v_mul_f32_e32 v10, 0xbfb8aa3b, v8
	v_exp_f32_e32 v10, v10
	v_mul_f32_e32 v9, v60, v0
	v_add_f32_e32 v10, 1.0, v10
	v_rcp_f32_e32 v10, v10
	s_nop 0
	v_mul_f32_e32 v8, v8, v10
	v_mul_f32_e32 v8, v9, v8
	v_mul_f32_e32 v9, v48, v0
	v_mul_f32_e32 v10, 0xbfb8aa3b, v9
	v_exp_f32_e32 v10, v10
	v_mul_f32_e32 v0, v56, v0
	v_add_f32_e32 v10, 1.0, v10
	v_rcp_f32_e32 v10, v10
	s_nop 0
	v_mul_f32_e32 v9, v9, v10
	v_mul_f32_e32 v0, v0, v9
; __device__ __forceinline__ u32 pack2(float a, float b) { return (u32)f2bf(a) | ((u32)f2bf(b) << 16); }
; __device__ __forceinline__ float sigmoidf_(float x) { return __builtin_amdgcn_rcpf(1.f + __expf(-x)); }
; __device__ __forceinline__ void gemm_tile(const GemmArgs& ga, int wgid, int next_wgid, bool prefetched, u16* shm, unsigned char* ws, int wv_) {
;     ...
;   if (epi == EPI_SWIGLU) {
;     const int oc = pn * HALF + (wc * 16 + fr) * 2;
;     float sc[2][4][4];
;     _Pragma("unroll") for (int ai = 0; ai < 2; ++ai)
;       _Pragma("unroll") for (int m = 0; m < 4; ++m)
;         _Pragma("unroll") for (int j = 0; j < 4; ++j) sc[ai][m][j] = e_ss[rbase + ai * HALF + m * 16 + j];
;     _Pragma("unroll") for (int ai = 0; ai < 2; ++ai)
;       _Pragma("unroll") for (int m = 0; m < 4; ++m)
;         _Pragma("unroll") for (int j = 0; j < 4; ++j) {
;           int row = rbase + ai * HALF + m * 16 + j;
;           float s = rsqrtf(sc[ai][m][j] * (1.f / D_) + 1e-6f);
;           float h2[2];
;           _Pragma("unroll") for (int n = 0; n < 2; ++n) {
;             float a1 = acc[ai][0][m][n][j] * s, a3 = acc[ai][1][m][n][j] * s;
;             h2[n] = a1 * sigmoidf_(a1) * a3;
;           }
;           *(u32*)(e_outb + (size_t)row * F_ + oc) = pack2(h2[0], h2[1]);
;         }
	v_cvt_pk_bf16_f32 v0, v8, v0
	global_store_dword v[64:65], v0, off
	v_rsq_f32_e32 v0, v1
	s_nop 0
	v_mul_f32_e32 v1, v53, v0
	v_mul_f32_e32 v9, 0xbfb8aa3b, v1
	v_exp_f32_e32 v9, v9
	v_mul_f32_e32 v8, v61, v0
	v_mad_i64_i32 v[52:53], s[2:3], v147, s8, v[128:129]
	v_add_f32_e32 v9, 1.0, v9
	v_rcp_f32_e32 v9, v9
	s_nop 0
	v_mul_f32_e32 v1, v1, v9
	v_mul_f32_e32 v1, v8, v1
	v_mul_f32_e32 v8, v49, v0
	v_mul_f32_e32 v9, 0xbfb8aa3b, v8
	v_exp_f32_e32 v9, v9
	v_mul_f32_e32 v0, v57, v0
	v_add_f32_e32 v9, 1.0, v9
	v_rcp_f32_e32 v9, v9
	s_nop 0
	v_mul_f32_e32 v8, v8, v9
	v_mul_f32_e32 v0, v0, v8
	v_cvt_pk_bf16_f32 v8, v1, v0
	v_mad_i64_i32 v[0:1], s[2:3], v150, s8, v[128:129]
	global_store_dword v[0:1], v8, off
	v_rsq_f32_e32 v2, v2
	v_mad_i64_i32 v[0:1], s[2:3], v149, s8, v[128:129]
	v_mul_f32_e32 v8, v54, v2
	v_mul_f32_e32 v10, 0xbfb8aa3b, v8
	v_exp_f32_e32 v10, v10
	v_mul_f32_e32 v9, v62, v2
	v_add_f32_e32 v10, 1.0, v10
	v_rcp_f32_e32 v10, v10
	s_nop 0
	v_mul_f32_e32 v8, v8, v10
	v_mul_f32_e32 v8, v9, v8
	v_mul_f32_e32 v9, v50, v2
	v_mul_f32_e32 v10, 0xbfb8aa3b, v9
	v_exp_f32_e32 v10, v10
	v_mul_f32_e32 v2, v58, v2
	v_add_f32_e32 v10, 1.0, v10
	v_rcp_f32_e32 v10, v10
	s_nop 0
	v_mul_f32_e32 v9, v9, v10
	v_mul_f32_e32 v2, v2, v9
	v_cvt_pk_bf16_f32 v2, v8, v2
	global_store_dword v[0:1], v2, off
	v_rsq_f32_e32 v0, v3
	s_nop 0
	v_mul_f32_e32 v1, v55, v0
	v_mul_f32_e32 v3, 0xbfb8aa3b, v1
	v_exp_f32_e32 v3, v3
	v_mul_f32_e32 v2, v63, v0
	v_add_f32_e32 v3, 1.0, v3
	v_rcp_f32_e32 v3, v3
	s_nop 0
	v_mul_f32_e32 v1, v1, v3
	v_mul_f32_e32 v1, v2, v1
	v_mul_f32_e32 v2, v51, v0
	v_mov_b64_e32 v[48:49], v[228:229]
	v_mov_b64_e32 v[50:51], v[230:231]
	v_mul_f32_e32 v3, 0xbfb8aa3b, v2
	v_exp_f32_e32 v3, v3
	v_mul_f32_e32 v0, v59, v0
	v_add_f32_e32 v3, 1.0, v3
	v_rcp_f32_e32 v3, v3
	s_nop 0
	v_mul_f32_e32 v2, v2, v3
	v_mul_f32_e32 v0, v0, v2
	v_cvt_pk_bf16_f32 v2, v1, v0
	v_mad_i64_i32 v[0:1], s[2:3], v148, s8, v[128:129]
	global_store_dword v[0:1], v2, off
	v_pk_fma_f32 v[0:1], v[48:49], s[12:13], v[130:131] op_sel_hi:[1,0,0]
	s_nop 0
	s_nop 0
	v_rsq_f32_e32 v0, v0
	s_nop 0
	v_mul_f32_e32 v2, v36, v0
	v_mul_f32_e32 v8, 0xbfb8aa3b, v2
	v_exp_f32_e32 v8, v8
	v_mul_f32_e32 v3, v44, v0
	v_add_f32_e32 v8, 1.0, v8
	v_rcp_f32_e32 v8, v8
	s_nop 0
	v_mul_f32_e32 v2, v2, v8
	v_mul_f32_e32 v2, v3, v2
	v_mul_f32_e32 v3, v32, v0
	v_mul_f32_e32 v8, 0xbfb8aa3b, v3
	v_exp_f32_e32 v8, v8
	v_mul_f32_e32 v0, v40, v0
	v_add_f32_e32 v8, 1.0, v8
	v_rcp_f32_e32 v8, v8
	s_nop 0
	v_mul_f32_e32 v3, v3, v8
	v_mul_f32_e32 v0, v0, v3
	v_cvt_pk_bf16_f32 v0, v2, v0
	global_store_dword v[52:53], v0, off
	v_rsq_f32_e32 v0, v1
	s_nop 0
	v_mul_f32_e32 v1, v37, v0
	v_mul_f32_e32 v3, 0xbfb8aa3b, v1
	v_exp_f32_e32 v3, v3
	v_mul_f32_e32 v2, v45, v0
	v_add_f32_e32 v3, 1.0, v3
	v_rcp_f32_e32 v3, v3
	s_nop 0
	v_mul_f32_e32 v1, v1, v3
	v_mul_f32_e32 v1, v2, v1
	v_mul_f32_e32 v2, v33, v0
	v_mul_f32_e32 v3, 0xbfb8aa3b, v2
	v_exp_f32_e32 v3, v3
	v_mul_f32_e32 v0, v41, v0
	v_mad_i64_i32 v[32:33], s[2:3], v143, s8, v[128:129]
	v_add_f32_e32 v3, 1.0, v3
	v_rcp_f32_e32 v3, v3
	s_nop 0
	v_mul_f32_e32 v2, v2, v3
	v_mul_f32_e32 v0, v0, v2
	v_cvt_pk_bf16_f32 v2, v1, v0
	v_mad_i64_i32 v[0:1], s[2:3], v146, s8, v[128:129]
	global_store_dword v[0:1], v2, off
	v_pk_fma_f32 v[2:3], v[50:51], s[12:13], v[130:131] op_sel_hi:[1,0,0]
	v_mad_i64_i32 v[0:1], s[2:3], v145, s8, v[128:129]
	s_nop 0
	v_rsq_f32_e32 v2, v2
	s_nop 0
	v_mul_f32_e32 v8, v38, v2
	v_mul_f32_e32 v10, 0xbfb8aa3b, v8
	v_exp_f32_e32 v10, v10
	v_mul_f32_e32 v9, v46, v2
	v_add_f32_e32 v10, 1.0, v10
	v_rcp_f32_e32 v10, v10
	s_nop 0
	v_mul_f32_e32 v8, v8, v10
	v_mul_f32_e32 v8, v9, v8
	v_mul_f32_e32 v9, v34, v2
	v_mul_f32_e32 v10, 0xbfb8aa3b, v9
	v_exp_f32_e32 v10, v10
	v_mul_f32_e32 v2, v42, v2
	v_add_f32_e32 v10, 1.0, v10
	v_rcp_f32_e32 v10, v10
	s_nop 0
	v_mul_f32_e32 v9, v9, v10
	v_mul_f32_e32 v2, v2, v9
	v_cvt_pk_bf16_f32 v2, v8, v2
	global_store_dword v[0:1], v2, off
	v_rsq_f32_e32 v0, v3
	s_nop 0
	v_mul_f32_e32 v1, v39, v0
	v_mul_f32_e32 v3, 0xbfb8aa3b, v1
	v_exp_f32_e32 v3, v3
	v_mul_f32_e32 v2, v47, v0
	v_add_f32_e32 v3, 1.0, v3
	v_rcp_f32_e32 v3, v3
	s_nop 0
	v_mul_f32_e32 v1, v1, v3
	v_mul_f32_e32 v1, v2, v1
	v_mul_f32_e32 v2, v35, v0
	v_mul_f32_e32 v3, 0xbfb8aa3b, v2
	v_exp_f32_e32 v3, v3
	v_mul_f32_e32 v0, v43, v0
	v_add_f32_e32 v3, 1.0, v3
	v_rcp_f32_e32 v3, v3
	s_nop 0
	v_mul_f32_e32 v2, v2, v3
	v_mul_f32_e32 v0, v0, v2
	v_cvt_pk_bf16_f32 v2, v1, v0
	v_mad_i64_i32 v[0:1], s[2:3], v144, s8, v[128:129]
	global_store_dword v[0:1], v2, off
	v_mov_b64_e32 v[0:1], v[232:233]
	v_mov_b64_e32 v[2:3], v[234:235]
	v_pk_fma_f32 v[0:1], v[0:1], s[12:13], v[130:131] op_sel_hi:[1,0,0]
	s_nop 0
	v_pk_fma_f32 v[2:3], v[2:3], s[12:13], v[130:131] op_sel_hi:[1,0,0]
	v_rsq_f32_e32 v0, v0
	s_nop 0
	v_mul_f32_e32 v8, v20, v0
	v_mul_f32_e32 v10, 0xbfb8aa3b, v8
	v_exp_f32_e32 v10, v10
	v_mul_f32_e32 v9, v244, v0
	v_add_f32_e32 v10, 1.0, v10
; __device__ __forceinline__ u32 pack2(float a, float b) { return (u32)f2bf(a) | ((u32)f2bf(b) << 16); }
; __device__ __forceinline__ float sigmoidf_(float x) { return __builtin_amdgcn_rcpf(1.f + __expf(-x)); }
; __device__ __forceinline__ void gemm_tile(const GemmArgs& ga, int wgid, int next_wgid, bool prefetched, u16* shm, unsigned char* ws, int wv_) {
;     ...
;   if (epi == EPI_SWIGLU) {
;     const int oc = pn * HALF + (wc * 16 + fr) * 2;
;     float sc[2][4][4];
;     _Pragma("unroll") for (int ai = 0; ai < 2; ++ai)
;       _Pragma("unroll") for (int m = 0; m < 4; ++m)
;         _Pragma("unroll") for (int j = 0; j < 4; ++j) sc[ai][m][j] = e_ss[rbase + ai * HALF + m * 16 + j];
;     _Pragma("unroll") for (int ai = 0; ai < 2; ++ai)
;       _Pragma("unroll") for (int m = 0; m < 4; ++m)
;         _Pragma("unroll") for (int j = 0; j < 4; ++j) {
;           int row = rbase + ai * HALF + m * 16 + j;
;           float s = rsqrtf(sc[ai][m][j] * (1.f / D_) + 1e-6f);
;           float h2[2];
;           _Pragma("unroll") for (int n = 0; n < 2; ++n) {
;             float a1 = acc[ai][0][m][n][j] * s, a3 = acc[ai][1][m][n][j] * s;
;             h2[n] = a1 * sigmoidf_(a1) * a3;
;           }
;           *(u32*)(e_outb + (size_t)row * F_ + oc) = pack2(h2[0], h2[1]);
;         }
	v_rcp_f32_e32 v10, v10
	s_nop 0
	v_mul_f32_e32 v8, v8, v10
	v_mul_f32_e32 v8, v9, v8
	v_mul_f32_e32 v9, v240, v0
	v_mul_f32_e32 v10, 0xbfb8aa3b, v9
	v_exp_f32_e32 v10, v10
	v_mul_f32_e32 v0, v24, v0
	v_add_f32_e32 v10, 1.0, v10
	v_rcp_f32_e32 v10, v10
	s_nop 0
	v_mul_f32_e32 v9, v9, v10
	v_mul_f32_e32 v0, v0, v9
	v_cvt_pk_bf16_f32 v0, v8, v0
	global_store_dword v[32:33], v0, off
	v_rsq_f32_e32 v0, v1
	s_nop 0
	v_mul_f32_e32 v1, v21, v0
	v_mul_f32_e32 v9, 0xbfb8aa3b, v1
	v_exp_f32_e32 v9, v9
	v_mul_f32_e32 v8, v245, v0
	v_mad_i64_i32 v[20:21], s[2:3], v139, s8, v[128:129]
	v_add_f32_e32 v9, 1.0, v9
	v_rcp_f32_e32 v9, v9
	s_nop 0
	v_mul_f32_e32 v1, v1, v9
	v_mul_f32_e32 v1, v8, v1
	v_mul_f32_e32 v8, v241, v0
	v_mul_f32_e32 v9, 0xbfb8aa3b, v8
	v_exp_f32_e32 v9, v9
	v_mul_f32_e32 v0, v25, v0
	v_add_f32_e32 v9, 1.0, v9
	v_rcp_f32_e32 v9, v9
	s_nop 0
	v_mul_f32_e32 v8, v8, v9
	v_mul_f32_e32 v0, v0, v8
	v_cvt_pk_bf16_f32 v8, v1, v0
	v_mad_i64_i32 v[0:1], s[2:3], v142, s8, v[128:129]
	global_store_dword v[0:1], v8, off
	v_rsq_f32_e32 v2, v2
	v_mad_i64_i32 v[0:1], s[2:3], v141, s8, v[128:129]
	v_mul_f32_e32 v8, v22, v2
	v_mul_f32_e32 v10, 0xbfb8aa3b, v8
	v_exp_f32_e32 v10, v10
	v_mul_f32_e32 v9, v246, v2
	v_add_f32_e32 v10, 1.0, v10
	v_rcp_f32_e32 v10, v10
	s_nop 0
	v_mul_f32_e32 v8, v8, v10
	v_mul_f32_e32 v8, v9, v8
	v_mul_f32_e32 v9, v242, v2
	v_mul_f32_e32 v10, 0xbfb8aa3b, v9
	v_exp_f32_e32 v10, v10
	v_mul_f32_e32 v2, v26, v2
	v_add_f32_e32 v10, 1.0, v10
	v_rcp_f32_e32 v10, v10
	s_nop 0
	v_mul_f32_e32 v9, v9, v10
	v_mul_f32_e32 v2, v2, v9
	v_cvt_pk_bf16_f32 v2, v8, v2
	global_store_dword v[0:1], v2, off
	v_rsq_f32_e32 v0, v3
	s_nop 0
	v_mul_f32_e32 v1, v23, v0
	v_mul_f32_e32 v3, 0xbfb8aa3b, v1
	v_exp_f32_e32 v3, v3
	v_mul_f32_e32 v2, v247, v0
	v_add_f32_e32 v3, 1.0, v3
	v_rcp_f32_e32 v3, v3
	s_nop 0
	v_mul_f32_e32 v1, v1, v3
	v_mul_f32_e32 v1, v2, v1
	v_mul_f32_e32 v2, v243, v0
	v_mul_f32_e32 v3, 0xbfb8aa3b, v2
	v_exp_f32_e32 v3, v3
	v_mul_f32_e32 v0, v27, v0
	v_add_f32_e32 v3, 1.0, v3
	v_rcp_f32_e32 v3, v3
	s_nop 0
	v_mul_f32_e32 v2, v2, v3
	v_mul_f32_e32 v0, v0, v2
	v_cvt_pk_bf16_f32 v2, v1, v0
	v_mad_i64_i32 v[0:1], s[2:3], v140, s8, v[128:129]
	global_store_dword v[0:1], v2, off
	v_pk_fma_f32 v[0:1], v[16:17], s[12:13], v[130:131] op_sel_hi:[1,0,0]
	s_nop 0
	s_nop 0
	v_rsq_f32_e32 v0, v0
	s_nop 0
	v_mul_f32_e32 v2, v204, v0
	v_mul_f32_e32 v8, 0xbfb8aa3b, v2
	v_exp_f32_e32 v8, v8
	v_mul_f32_e32 v3, v12, v0
	v_add_f32_e32 v8, 1.0, v8
	v_rcp_f32_e32 v8, v8
	s_nop 0
	v_mul_f32_e32 v2, v2, v8
	v_mul_f32_e32 v2, v3, v2
	v_mul_f32_e32 v3, v182, v0
	v_mul_f32_e32 v0, v4, v0
	v_mul_f32_e32 v4, 0xbfb8aa3b, v3
	v_exp_f32_e32 v4, v4
	s_nop 0
	v_add_f32_e32 v4, 1.0, v4
	v_rcp_f32_e32 v4, v4
	s_nop 0
	v_mul_f32_e32 v3, v3, v4
	v_mul_f32_e32 v0, v0, v3
	v_cvt_pk_bf16_f32 v0, v2, v0
	global_store_dword v[20:21], v0, off
	v_rsq_f32_e32 v0, v1
	s_nop 0
	v_mul_f32_e32 v1, v205, v0
	v_mul_f32_e32 v3, 0xbfb8aa3b, v1
	v_exp_f32_e32 v3, v3
	v_mul_f32_e32 v2, v13, v0
	v_add_f32_e32 v3, 1.0, v3
	v_rcp_f32_e32 v3, v3
	s_nop 0
	v_mul_f32_e32 v1, v1, v3
	v_mul_f32_e32 v1, v2, v1
	v_mul_f32_e32 v2, v183, v0
	v_mul_f32_e32 v3, 0xbfb8aa3b, v2
	v_exp_f32_e32 v3, v3
	v_mul_f32_e32 v0, v5, v0
	v_add_f32_e32 v3, 1.0, v3
	v_rcp_f32_e32 v3, v3
	s_nop 0
	v_mul_f32_e32 v2, v2, v3
	v_mul_f32_e32 v0, v0, v2
	v_cvt_pk_bf16_f32 v2, v1, v0
	v_mad_i64_i32 v[0:1], s[2:3], v138, s8, v[128:129]
	global_store_dword v[0:1], v2, off
	v_pk_fma_f32 v[2:3], v[18:19], s[12:13], v[130:131] op_sel_hi:[1,0,0]
	v_mad_i64_i32 v[0:1], s[2:3], v137, s8, v[128:129]
	s_nop 0
	v_rsq_f32_e32 v2, v2
	s_nop 0
	v_mul_f32_e32 v4, v206, v2
	v_mul_f32_e32 v8, 0xbfb8aa3b, v4
	v_exp_f32_e32 v8, v8
	v_mul_f32_e32 v5, v14, v2
	v_add_f32_e32 v8, 1.0, v8
	v_rcp_f32_e32 v8, v8
	s_nop 0
	v_mul_f32_e32 v4, v4, v8
	v_mul_f32_e32 v4, v5, v4
	v_mul_f32_e32 v5, v184, v2
	v_mul_f32_e32 v2, v6, v2
	v_mul_f32_e32 v6, 0xbfb8aa3b, v5
	v_exp_f32_e32 v6, v6
	s_nop 0
	v_add_f32_e32 v6, 1.0, v6
	v_rcp_f32_e32 v6, v6
	s_nop 0
	v_mul_f32_e32 v5, v5, v6
	v_mul_f32_e32 v2, v2, v5
	v_cvt_pk_bf16_f32 v2, v4, v2
	global_store_dword v[0:1], v2, off
	v_rsq_f32_e32 v0, v3
	s_nop 0
	v_mul_f32_e32 v1, v207, v0
	v_mul_f32_e32 v3, 0xbfb8aa3b, v1
	v_exp_f32_e32 v3, v3
	v_mul_f32_e32 v2, v15, v0
	v_add_f32_e32 v3, 1.0, v3
	v_rcp_f32_e32 v3, v3
	s_nop 0
	v_mul_f32_e32 v1, v1, v3
	v_mul_f32_e32 v1, v2, v1
	v_mul_f32_e32 v2, v185, v0
	v_mul_f32_e32 v3, 0xbfb8aa3b, v2
	v_exp_f32_e32 v3, v3
	v_mul_f32_e32 v0, v7, v0
	v_add_f32_e32 v3, 1.0, v3
	v_rcp_f32_e32 v3, v3
	s_nop 0
	v_mul_f32_e32 v2, v2, v3
	v_mul_f32_e32 v0, v0, v2
	v_bfe_u32 v2, v1, 16, 1
	v_add3_u32 v1, v1, v2, s48
	v_bfe_u32 v2, v0, 16, 1
	v_lshrrev_b32_e32 v1, 16, v1
	v_add3_u32 v0, v0, v2, s48
	v_and_or_b32 v2, v0, s97, v1
	v_mad_i64_i32 v[0:1], s[2:3], v136, s8, v[128:129]
	global_store_dword v[0:1], v2, off
	s_mov_b32 s101, 0x53574947
	s_branch .LBB0_501
